# k28 + GLA stage-1 loop: the 4 row-sum shuffle chains issued interleaved (8 serialized LDS round trips -> 2)
# speedup vs baseline: 1.0144x; 1.0047x over previous
; template <int MODE>
; __device__ __forceinline__ void gla_item(const Frame& F, int hh, int grp, const bf16_t* BB, const float* BZ, const float* w2g, const float* biasg, const float* gn, bf16_t* SLOC, float* DG, bf16_t* Hout) {
;     ...
;         bf16x8 vfr[2][2];
; #pragma unroll
;         for (int kk = 0; kk < 2; ++kk)
; #pragma unroll
;             for (int nt = 0; nt < 2; ++nt) {
;                 const LAS unsigned char* vp = L + GL_V + (32 * kk + 8 * g + q4) * GL_VST + (32 * w + 16 * nt + 4 * p4) * 2;
;                 const v4i16_t lo = vtr(vp), hi = vtr(vp + 4 * GL_VST);
;                 vfr[kk][nt] = __builtin_shufflevector(lo, hi, 0, 1, 2, 3, 4, 5, 6, 7);
;             }
;         if (MODE == 1) {
;             {
;                 const int it = w >> 1;
; #pragma unroll
;                 for (int jj = 0; jj < 2; ++jj) {
;                     const int jt = 2 * (w & 1) + jj;
;                     f32x4 a4 = (f32x4){0.f, 0.f, 0.f, 0.f};
; #pragma unroll
;                     for (int kk = 0; kk < 4; ++kk) {
;                         const bf16x8 a = *(const LAS bf16x8*)(L + GL_QT + (16 * it + c) * GL_ST + (8 * g + 32 * kk) * 2);
;                         const bf16x8 b = *(const LAS bf16x8*)(L + GL_KH + (16 * jt + c) * GL_ST + (8 * g + 32 * kk) * 2);
;                         a4 = MFMA16(a, b, a4);
;                     }
; #pragma unroll
;                     for (int j = 0; j < 4; ++j) { const int i = 16 * it + 4 * g + j, jc = 16 * jt + c;
;                         *(LAS bf16_t*)(L + GL_AM + i * GL_AST + jc * 2) = (bf16_t)f2bf(jc <= i ? a4[j] : 0.f); }
;                 }
;             }
;             __syncthreads();
;             f32x4 o[2][4];
; #pragma unroll
;             for (int mt = 0; mt < 2; ++mt)
; #pragma unroll
;                 for (int it = 0; it < 4; ++it) o[mt][it] = (f32x4){0.f, 0.f, 0.f, 0.f};
; #pragma unroll
;             for (int kq = 0; kq < 4; ++kq) {
;                 bf16x8 qb[4];
; #pragma unroll
;                 for (int it = 0; it < 4; ++it) {
;                     const LAS unsigned char* qp = L + GL_QT + (16 * it + c) * GL_ST + (32 * kq + 4 * g) * 2;
;                     const u32x2 lo = *(const LAS u32x2*)qp, hi = *(const LAS u32x2*)(qp + 32);
;                     u32x4 t4; t4.x = lo.x; t4.y = lo.y; t4.z = hi.x; t4.w = hi.y; qb[it] = __builtin_bit_cast(bf16x8, t4);
;                 }
; #pragma unroll
.LBB0_617:
	s_or_b64 exec, exec, s[0:1]
	s_waitcnt lgkmcnt(0)
	s_barrier
	ds_read_b128 v[64:67], v233
	ds_read_b128 v[68:71], v234 offset:17408
	ds_read_b128 v[72:75], v233 offset:64
	ds_read_b128 v[76:79], v234 offset:17472
	s_waitcnt lgkmcnt(2)
	v_mfma_f32_16x16x32_bf16 v[64:67], v[64:67], v[68:71], 0
	ds_read_b128 v[68:71], v233 offset:128
	ds_read_b128 v[80:83], v234 offset:17536
	ds_read_b128 v[84:87], v233 offset:192
	v_add_u32_e32 v88, v227, v231
	v_add_u32_e32 v180, 0x1000, v238
	s_waitcnt lgkmcnt(3)
	v_mfma_f32_16x16x32_bf16 v[64:67], v[72:75], v[76:79], v[64:67]
	ds_read_b64_tr_b16 v[78:79], v88 offset:55424
	ds_read_b64_tr_b16 v[76:77], v88 offset:53248
	ds_read_b64_tr_b16 v[74:75], v88 offset:55456
	ds_read_b64_tr_b16 v[72:73], v88 offset:53280
	ds_read_b128 v[88:91], v234 offset:17600
	v_add_u32_e32 v181, 0x2000, v238
	v_add_u32_e32 v182, 0x3000, v238
	s_waitcnt lgkmcnt(6)
	v_mfma_f32_16x16x32_bf16 v[80:83], v[68:71], v[80:83], v[64:67]
	s_nop 2
	ds_read_b64_tr_b16 v[66:67], v232 offset:55424
	ds_read_b64_tr_b16 v[64:65], v232 offset:53248
	ds_read_b64_tr_b16 v[70:71], v232 offset:55456
	ds_read_b64_tr_b16 v[68:69], v232 offset:53280
	v_cvt_pk_bf16_f32 v112, v4, v5
	v_cvt_pk_bf16_f32 v113, v6, v7
	s_waitcnt lgkmcnt(4)
	v_mfma_f32_16x16x32_bf16 v[80:83], v[84:87], v[88:91], v[80:83]
	v_cvt_pk_bf16_f32 v114, v8, v9
	v_cvt_pk_bf16_f32 v115, v10, v11
	s_nop 5
	v_cndmask_b32_e64 v80, v80, 0, s[10:11]
	v_bfe_u32 v84, v80, 16, 1
	v_cndmask_b32_e64 v81, v81, 0, s[12:13]
	v_add3_u32 v80, v80, v84, s29
	ds_write_b16_d16_hi v235, v80
	v_bfe_u32 v80, v81, 16, 1
	v_add3_u32 v80, v81, v80, s29
	ds_write_b16_d16_hi v235, v80 offset:144
	v_cndmask_b32_e64 v80, v82, 0, s[14:15]
	v_bfe_u32 v81, v80, 16, 1
	v_add3_u32 v80, v80, v81, s29
	ds_write_b16_d16_hi v235, v80 offset:288
	v_cndmask_b32_e64 v80, v83, 0, s[16:17]
	v_bfe_u32 v81, v80, 16, 1
	v_add3_u32 v80, v80, v81, s29
	ds_write_b16_d16_hi v235, v80 offset:432
	ds_read_b128 v[80:83], v233
	ds_read_b128 v[84:87], v233 offset:64
	ds_read_b128 v[88:91], v236 offset:17408
	ds_read_b128 v[92:95], v236 offset:17472
	s_waitcnt lgkmcnt(1)
	v_mfma_f32_16x16x32_bf16 v[80:83], v[80:83], v[88:91], 0
	ds_read_b128 v[88:91], v233 offset:128
	s_waitcnt lgkmcnt(1)
	v_mfma_f32_16x16x32_bf16 v[80:83], v[84:87], v[92:95], v[80:83]
	ds_read_b128 v[84:87], v233 offset:192
	ds_read_b128 v[92:95], v236 offset:17536
	ds_read_b128 v[96:99], v236 offset:17600
	s_waitcnt lgkmcnt(1)
	v_mfma_f32_16x16x32_bf16 v[80:83], v[88:91], v[92:95], v[80:83]
	s_waitcnt lgkmcnt(0)
	v_mfma_f32_16x16x32_bf16 v[80:83], v[84:87], v[96:99], v[80:83]
	v_cvt_pk_bf16_f32 v86, v20, v21
	v_cvt_pk_bf16_f32 v87, v22, v23
	s_nop 5
	v_cndmask_b32_e64 v80, v80, 0, s[18:19]
	v_cndmask_b32_e64 v81, v81, 0, s[20:21]
	v_bfe_u32 v84, v80, 16, 1
	v_bfe_u32 v85, v81, 16, 1
	v_add3_u32 v80, v80, v84, s29
	ds_write_b16_d16_hi v237, v80
	v_add3_u32 v80, v81, v85, s29
	ds_write_b16_d16_hi v237, v80 offset:144
	v_cndmask_b32_e64 v80, v82, 0, s[22:23]
	v_bfe_u32 v81, v80, 16, 1
	v_add3_u32 v80, v80, v81, s29
	ds_write_b16_d16_hi v237, v80 offset:288
	v_cndmask_b32_e64 v80, v83, 0, s[24:25]
	v_bfe_u32 v81, v80, 16, 1
	v_add3_u32 v80, v80, v81, s29
	ds_write_b16_d16_hi v237, v80 offset:432
	s_waitcnt lgkmcnt(0)
	s_barrier
	ds_read2_b64 v[80:83], v238 offset1:4
	v_cvt_pk_bf16_f32 v84, v0, v1
	v_cvt_pk_bf16_f32 v85, v2, v3
	ds_read2_b64 v[92:95], v180 offset0:32 offset1:36
	ds_read2_b64 v[100:103], v181 offset0:64 offset1:68
	ds_read2_b64 v[108:111], v182 offset0:96 offset1:100
	s_waitcnt lgkmcnt(3)
	v_mfma_f32_16x16x32_bf16 v[88:91], v[84:87], v[80:83], 0
	s_waitcnt lgkmcnt(2)
	v_mfma_f32_16x16x32_bf16 v[96:99], v[84:87], v[92:95], 0
	s_waitcnt lgkmcnt(1)
	v_mfma_f32_16x16x32_bf16 v[104:107], v[84:87], v[100:103], 0
	s_waitcnt lgkmcnt(0)
	v_mfma_f32_16x16x32_bf16 v[84:87], v[84:87], v[108:111], 0
	v_mfma_f32_16x16x32_bf16 v[80:83], v[112:115], v[80:83], 0
	v_mfma_f32_16x16x32_bf16 v[92:95], v[112:115], v[92:95], 0
	v_mfma_f32_16x16x32_bf16 v[100:103], v[112:115], v[100:103], 0
	v_mfma_f32_16x16x32_bf16 v[108:111], v[112:115], v[108:111], 0
	ds_read2_b64 v[112:115], v238 offset0:8 offset1:12
	v_cvt_pk_bf16_f32 v116, v28, v29
	v_cvt_pk_bf16_f32 v117, v30, v31
	v_cvt_pk_bf16_f32 v118, v36, v37
	v_cvt_pk_bf16_f32 v119, v38, v39
	ds_read2_b64 v[168:171], v180 offset0:40 offset1:44
	ds_read2_b64 v[172:175], v181 offset0:72 offset1:76
	ds_read2_b64 v[176:179], v182 offset0:104 offset1:108
	s_waitcnt lgkmcnt(3)
	v_mfma_f32_16x16x32_bf16 v[88:91], v[116:119], v[112:115], v[88:91]
	s_waitcnt lgkmcnt(2)
	v_mfma_f32_16x16x32_bf16 v[96:99], v[116:119], v[168:171], v[96:99]
	s_waitcnt lgkmcnt(1)
	v_mfma_f32_16x16x32_bf16 v[104:107], v[116:119], v[172:175], v[104:107]
	s_waitcnt lgkmcnt(0)
	v_mfma_f32_16x16x32_bf16 v[84:87], v[116:119], v[176:179], v[84:87]
	v_cvt_pk_bf16_f32 v116, v12, v13
	v_cvt_pk_bf16_f32 v117, v14, v15
	v_cvt_pk_bf16_f32 v118, v16, v17
	v_cvt_pk_bf16_f32 v119, v18, v19
	s_nop 1
	v_mfma_f32_16x16x32_bf16 v[80:83], v[116:119], v[112:115], v[80:83]
	v_mfma_f32_16x16x32_bf16 v[92:95], v[116:119], v[168:171], v[92:95]
	v_mfma_f32_16x16x32_bf16 v[100:103], v[116:119], v[172:175], v[100:103]
	v_mfma_f32_16x16x32_bf16 v[108:111], v[116:119], v[176:179], v[108:111]
	ds_read2_b64 v[112:115], v238 offset0:16 offset1:20
	v_cvt_pk_bf16_f32 v116, v44, v45
	v_cvt_pk_bf16_f32 v117, v46, v47
	v_cvt_pk_bf16_f32 v118, v52, v53
	v_cvt_pk_bf16_f32 v119, v54, v55
	ds_read2_b64 v[168:171], v180 offset0:48 offset1:52
	ds_read2_b64 v[172:175], v181 offset0:80 offset1:84
	ds_read2_b64 v[176:179], v182 offset0:112 offset1:116
	s_waitcnt lgkmcnt(3)
; #define LAS __attribute__((address_space(3)))
; #define MFMA16(a, b, c) __builtin_amdgcn_mfma_f32_16x16x32_bf16((a), (b), (c), 0, 0, 0)
; template <int MODE>
; __device__ __forceinline__ void gla_item(const Frame& F, int hh, int grp, const bf16_t* BB, const float* BZ, const float* w2g, const float* biasg, const float* gn, bf16_t* SLOC, float* DG, bf16_t* Hout) {
;     ...
; #pragma unroll
;             for (int kk = 0; kk < 2; ++kk) {
; #pragma unroll
;                 for (int it = 0; it < 4; ++it) {
;                     const bf16x8 ab = *(const LAS bf16x8*)(L + GL_AM + (16 * it + c) * GL_AST + (32 * kk + 8 * g) * 2);
; #pragma unroll
;                     for (int mt = 0; mt < 2; ++mt) o[mt][it] = MFMA16(vfr[kk][mt], ab, o[mt][it]);
;                 }
;                 __builtin_amdgcn_sched_barrier(0);
;             }
;             {
;                 LAS float* red = (LAS float*)(L + GL_RED);
;                 u32x2 bwv[2][2];
; #pragma unroll
;                 for (int it = 0; it < 2; ++it)
; #pragma unroll
;                     for (int mt = 0; mt < 2; ++mt) bwv[it][mt] = *(const u32x2*)(BB + (size_t)(t0 + 16 * it + c) * 3072 + 2048 + hh * 256 + 32 * w + 16 * mt + 4 * g);
;                 const f32x4 gv0 = *(const f32x4*)(gn + 32 * w + 4 * g), gv1 = *(const f32x4*)(gn + 32 * w + 16 + 4 * g);
; #pragma unroll
;                 for (int it = 0; it < 4; ++it) {
;                     float ss = 0.f;
; #pragma unroll
;                     for (int mt = 0; mt < 2; ++mt) ss += (o[mt][it][0] * o[mt][it][0] + o[mt][it][1] * o[mt][it][1]) + (o[mt][it][2] * o[mt][it][2] + o[mt][it][3] * o[mt][it][3]);
;                     ss += __shfl_xor(ss, 16); ss += __shfl_xor(ss, 32);
;                     if (g == 0) red[w * 64 + 16 * it + c] = ss;
;                 }
	v_mfma_f32_16x16x32_bf16 v[88:91], v[116:119], v[112:115], v[88:91]
	s_waitcnt lgkmcnt(2)
	v_mfma_f32_16x16x32_bf16 v[96:99], v[116:119], v[168:171], v[96:99]
	s_waitcnt lgkmcnt(1)
	v_mfma_f32_16x16x32_bf16 v[104:107], v[116:119], v[172:175], v[104:107]
	s_waitcnt lgkmcnt(0)
	v_mfma_f32_16x16x32_bf16 v[84:87], v[116:119], v[176:179], v[84:87]
	v_cvt_pk_bf16_f32 v116, v24, v25
	v_cvt_pk_bf16_f32 v117, v26, v27
	v_cvt_pk_bf16_f32 v118, v32, v33
	v_cvt_pk_bf16_f32 v119, v34, v35
	s_nop 1
	v_mfma_f32_16x16x32_bf16 v[80:83], v[116:119], v[112:115], v[80:83]
	v_mfma_f32_16x16x32_bf16 v[92:95], v[116:119], v[168:171], v[92:95]
	v_mfma_f32_16x16x32_bf16 v[100:103], v[116:119], v[172:175], v[100:103]
	v_mfma_f32_16x16x32_bf16 v[108:111], v[116:119], v[176:179], v[108:111]
	ds_read2_b64 v[112:115], v238 offset0:24 offset1:28
	v_cvt_pk_bf16_f32 v116, v56, v57
	v_cvt_pk_bf16_f32 v117, v58, v59
	v_cvt_pk_bf16_f32 v118, v60, v61
	v_cvt_pk_bf16_f32 v119, v62, v63
	ds_read2_b64 v[168:171], v180 offset0:56 offset1:60
	ds_read2_b64 v[172:175], v181 offset0:88 offset1:92
	ds_read2_b64 v[176:179], v182 offset0:120 offset1:124
	s_waitcnt lgkmcnt(3)
	v_mfma_f32_16x16x32_bf16 v[88:91], v[116:119], v[112:115], v[88:91]
	s_waitcnt lgkmcnt(2)
	v_mfma_f32_16x16x32_bf16 v[96:99], v[116:119], v[168:171], v[96:99]
	s_waitcnt lgkmcnt(1)
	v_mfma_f32_16x16x32_bf16 v[104:107], v[116:119], v[172:175], v[104:107]
	s_waitcnt lgkmcnt(0)
	v_mfma_f32_16x16x32_bf16 v[84:87], v[116:119], v[176:179], v[84:87]
	v_cvt_pk_bf16_f32 v116, v40, v41
	v_cvt_pk_bf16_f32 v117, v42, v43
	v_cvt_pk_bf16_f32 v118, v48, v49
	v_cvt_pk_bf16_f32 v119, v50, v51
	s_nop 1
	v_mfma_f32_16x16x32_bf16 v[80:83], v[116:119], v[112:115], v[80:83]
	v_mfma_f32_16x16x32_bf16 v[92:95], v[116:119], v[168:171], v[92:95]
	v_mfma_f32_16x16x32_bf16 v[100:103], v[116:119], v[172:175], v[100:103]
	v_mfma_f32_16x16x32_bf16 v[108:111], v[116:119], v[176:179], v[108:111]
	ds_read_b128 v[112:115], v239
	s_waitcnt lgkmcnt(0)
	v_mfma_f32_16x16x32_bf16 v[88:91], v[76:79], v[112:115], v[88:91]
	v_mfma_f32_16x16x32_bf16 v[80:83], v[72:75], v[112:115], v[80:83]
	ds_read_b128 v[112:115], v239 offset:2304
	s_waitcnt lgkmcnt(0)
	v_mfma_f32_16x16x32_bf16 v[96:99], v[76:79], v[112:115], v[96:99]
	v_mfma_f32_16x16x32_bf16 v[92:95], v[72:75], v[112:115], v[92:95]
	ds_read_b128 v[112:115], v239 offset:4608
	s_waitcnt lgkmcnt(0)
	v_mfma_f32_16x16x32_bf16 v[172:175], v[72:75], v[112:115], v[100:103]
	s_nop 2
	ds_read_b128 v[100:103], v239 offset:6912
	v_mfma_f32_16x16x32_bf16 v[168:171], v[76:79], v[112:115], v[104:107]
	s_waitcnt lgkmcnt(0)
	v_mfma_f32_16x16x32_bf16 v[84:87], v[76:79], v[100:103], v[84:87]
	v_mfma_f32_16x16x32_bf16 v[176:179], v[72:75], v[100:103], v[108:111]
	ds_read_b128 v[100:103], v239 offset:64
	s_waitcnt lgkmcnt(0)
	v_mfma_f32_16x16x32_bf16 v[112:115], v[68:71], v[100:103], v[80:83]
	s_nop 2
	ds_read_b128 v[80:83], v239 offset:2368
	v_mfma_f32_16x16x32_bf16 v[116:119], v[64:67], v[100:103], v[88:91]
	s_waitcnt lgkmcnt(0)
	v_mfma_f32_16x16x32_bf16 v[108:111], v[64:67], v[80:83], v[96:99]
	v_mfma_f32_16x16x32_bf16 v[104:107], v[68:71], v[80:83], v[92:95]
	ds_read_b128 v[80:83], v239 offset:4672
	s_waitcnt lgkmcnt(0)
	v_mfma_f32_16x16x32_bf16 v[100:103], v[64:67], v[80:83], v[168:171]
	v_mfma_f32_16x16x32_bf16 v[96:99], v[68:71], v[80:83], v[172:175]
	ds_read_b128 v[80:83], v239 offset:6976
	s_waitcnt lgkmcnt(0)
	v_mfma_f32_16x16x32_bf16 v[88:91], v[64:67], v[80:83], v[84:87]
	v_mfma_f32_16x16x32_bf16 v[80:83], v[68:71], v[80:83], v[176:179]
	v_add_u32_e32 v174, s83, v122
	s_nop 0
	v_mov_b64_e32 v[84:85], s[36:37]
	v_mad_i64_i32 v[86:87], s[0:1], v174, s94, v[84:85]
	v_lshl_add_u64 v[86:87], v[86:87], 0, s[90:91]
	s_lshl_b32 s38, s40, 1
	v_add_u32_e32 v180, 16, v174
	v_lshl_add_u64 v[86:87], v[86:87], 0, s[38:39]
	v_lshlrev_b64 v[172:173], 1, v[144:145]
	v_mad_i64_i32 v[84:85], s[0:1], v180, s94, v[84:85]
	v_lshl_add_u64 v[86:87], v[86:87], 0, v[172:173]
	v_lshl_add_u64 v[84:85], v[84:85], 0, s[90:91]
	v_lshl_add_u64 v[92:93], v[86:87], 0, s[44:45]
	v_add_co_u32_e32 v86, vcc, s95, v86
	v_lshl_add_u64 v[84:85], v[84:85], 0, s[38:39]
	s_nop 0
	v_addc_co_u32_e32 v87, vcc, 0, v87, vcc
	v_lshl_add_u64 v[84:85], v[84:85], 0, v[172:173]
	v_lshl_add_u64 v[94:95], v[84:85], 0, s[44:45]
	v_add_co_u32_e32 v84, vcc, s95, v84
	v_mul_f32_e32 v170, v117, v117
	s_nop 0
	v_addc_co_u32_e32 v85, vcc, 0, v85, vcc
	global_load_dwordx2 v[168:169], v[86:87], off
	global_load_dwordx2 v[178:179], v[84:85], off
	global_load_dwordx2 v[176:177], v[94:95], off offset:32
	global_load_dwordx2 v[194:195], v[92:93], off offset:32
	s_nop 0
	global_load_dwordx4 v[92:95], v[146:147], off
	global_load_dwordx4 v[84:87], v[146:147], off offset:64
	v_mul_f32_e32 v171, v119, v119
	v_fmac_f32_e32 v170, v116, v116
	v_fmac_f32_e32 v171, v118, v118
	v_add_f32_e32 v170, v170, v171
	v_mul_f32_e32 v171, v113, v113
	v_mul_f32_e32 v175, v115, v115
	v_fmac_f32_e32 v171, v112, v112
	v_fmac_f32_e32 v175, v114, v114
	v_add_f32_e32 v171, v171, v175
	v_add_f32_e32 v170, v170, v171
	v_mov_b32_e32 v182, v170
	v_mul_f32_e32 v170, v109, v109
	v_mul_f32_e32 v171, v111, v111
	v_fmac_f32_e32 v170, v108, v108
	v_fmac_f32_e32 v171, v110, v110
	v_add_f32_e32 v170, v170, v171
	v_mul_f32_e32 v171, v105, v105
	v_mul_f32_e32 v175, v107, v107
	v_fmac_f32_e32 v171, v104, v104
	v_fmac_f32_e32 v175, v106, v106
	v_add_f32_e32 v171, v171, v175
	v_add_f32_e32 v183, v170, v171
	v_mul_f32_e32 v170, v101, v101
	v_mul_f32_e32 v171, v103, v103
	v_fmac_f32_e32 v170, v100, v100
	v_fmac_f32_e32 v171, v102, v102
	v_add_f32_e32 v170, v170, v171
	v_mul_f32_e32 v171, v97, v97
	v_mul_f32_e32 v175, v99, v99
	v_fmac_f32_e32 v171, v96, v96
	v_fmac_f32_e32 v175, v98, v98
	v_add_f32_e32 v171, v171, v175
	v_add_f32_e32 v184, v170, v171
	v_mul_f32_e32 v170, v89, v89
	v_mul_f32_e32 v171, v91, v91
	v_fmac_f32_e32 v170, v88, v88
	v_fmac_f32_e32 v171, v90, v90
	v_add_f32_e32 v170, v170, v171
	v_mul_f32_e32 v171, v81, v81
	v_mul_f32_e32 v175, v83, v83
	v_fmac_f32_e32 v171, v80, v80
	v_fmac_f32_e32 v175, v82, v82
	v_add_f32_e32 v171, v171, v175
	v_add_f32_e32 v185, v170, v171
	ds_bpermute_b32 v186, v206, v182
	ds_bpermute_b32 v187, v206, v183
	ds_bpermute_b32 v188, v206, v184
	ds_bpermute_b32 v189, v206, v185
	s_waitcnt lgkmcnt(3)
	v_add_f32_e32 v182, v182, v186
	s_waitcnt lgkmcnt(2)
	v_add_f32_e32 v183, v183, v187
	s_waitcnt lgkmcnt(1)
	v_add_f32_e32 v184, v184, v188
	s_waitcnt lgkmcnt(0)
	v_add_f32_e32 v185, v185, v189
	ds_bpermute_b32 v186, v207, v182
	ds_bpermute_b32 v187, v207, v183
	ds_bpermute_b32 v188, v207, v184
	ds_bpermute_b32 v189, v207, v185
	s_and_saveexec_b64 s[0:1], s[8:9]
	s_cbranch_execz .LBB0_614
	s_waitcnt lgkmcnt(0)
	v_add_f32_e32 v182, v182, v186
	v_add_f32_e32 v183, v183, v187
	v_add_f32_e32 v184, v184, v188
	v_add_f32_e32 v185, v185, v189
	ds_write_b32 v229, v182
	ds_write_b32 v229, v183 offset:64
	ds_write_b32 v229, v184 offset:128
	ds_write_b32 v229, v185 offset:192
	s_branch .LBB0_614
